# GEMM1 tile order: 4-row groups with a per-XCD column rotation (9 column tiles per XCD) so XCDs do not walk the same weight panels in lockstep
# speedup vs baseline: 1.0135x; 1.0135x over previous
; __device__ __forceinline__ KP kargs() { KP q = (KP)__builtin_amdgcn_kernarg_segment_ptr(); asm volatile("" : "+s"(q)); return q; }
; __device__ __forceinline__ unsigned xb_ld(unsigned* p)              { return __hip_atomic_load(p, __ATOMIC_RELAXED, __HIP_MEMORY_SCOPE_AGENT); }
; #define REPS(i) for (int rep_ = 0; rep_ < (((REP_MASK >> (i)) & 1u) ? 2 : 1); ++rep_)
; __device__ __forceinline__ void xcd_barrier_complete(unsigned* bar, unsigned x, unsigned& nloc, unsigned& nx) {
;     const unsigned G = gridDim.x * gridDim.y * gridDim.z;
;     unsigned sum, cnt, mine, sp = 0u;
;     for (;;) {
;         sum = 0u; cnt = 0u; mine = 0u;
; #pragma unroll
;         for (unsigned j = 0; j < 16; ++j) { const unsigned c = xb_ld(&bar[XB_XCNT(j)]); sum += c; cnt += (c > 0u) ? 1u : 0u; mine = (j == x) ? c : mine; }
; __global__ void __launch_bounds__(512, 2) fwd_megakernel(Params p_unused) {
;     ...
;     const int vc = (int)bst[2];
;     for (int l = 0; l < DEPTH; ++l) {
;         const int pb = 1 + 6 * l; KP p = kargs(); unsigned char* ws = p->ws;
;         if (IN(pb + 0)) REPS(1) {
;             pg8::Gemm g{(const bf16_t*)(ws + WS_XB), (const bf16_t*)(ws + WS_WIN + l * SZ_WIN), SEQ, DIN, DM};
;             pg8::StaticOrder S; S.init(SEQ, DIN - 256, gridDim.x, vc);
;             pg8::EpiH E{(bf16_t*)(ws + WS_HM), (bf16_t*)(ws + WS_HG)};
;             pg8::gemm_phase<GEMM_ALIGN, GEMM_SP2>(lds, g, S, E);
.LBB0_212:
	s_add_i32 s3, 0, 0x23fc8
	v_mov_b32_e32 v0, s3
	s_waitcnt lgkmcnt(0)
	s_barrier
	ds_read_b32 v0, v0
	v_mov_b32_e32 v168, 1
	v_mov_b32_e32 v169, 0x3727c5ac
	v_mov_b64_e32 v[140:141], 0x1200
	v_mov_b64_e32 v[142:143], 0x11ff
	s_waitcnt lgkmcnt(0)
	v_readfirstlane_b32 s3, v0
	s_cmpk_lt_i32 s3, 0x1200
	s_cselect_b64 s[14:15], -1, 0
	s_ashr_i32 s13, s3, 31
	s_lshr_b32 s6, s13, 29
	s_add_i32 s6, s3, s6
	s_ashr_i32 s7, s6, 3
	s_and_b32 s6, s6, -8
	s_sub_i32 s6, s3, s6
	s_ashr_i32 s21, s72, 31
	s_add_u32 s48, s0, 0x3ab00200
	s_addc_u32 s49, s1, 0
	s_add_u32 s62, s0, 0x3ab00400
	s_addc_u32 s63, s1, 0
	s_add_u32 s64, s0, 0x3ab00500
	s_addc_u32 s65, s1, 0
	s_add_u32 s74, s0, 0x3ab00600
	s_addc_u32 s75, s1, 0
	s_add_u32 s10, s0, 0x3ab00700
	s_addc_u32 s11, s1, 0
	s_add_u32 s88, s0, 0x3ab00800
	s_addc_u32 s89, s1, 0
	s_add_u32 s94, s0, 0x3ab00900
	s_addc_u32 s95, s1, 0
	s_add_u32 s8, s0, 0x3ab00a00
	s_addc_u32 s9, s1, 0
	v_writelane_b32 v241, s8, 6
	v_mov_b32_e32 v170, 0x41f00000
	v_mov_b32_e32 v171, 0x4200
	v_writelane_b32 v241, s9, 7
	s_add_u32 s8, s0, 0x3ab00b00
	s_addc_u32 s9, s1, 0
	v_writelane_b32 v241, s8, 8
	v_mov_b32_e32 v173, 0xf149f2ca
	v_mov_b64_e32 v[144:145], 0x200
	v_writelane_b32 v241, s9, 9
	s_add_u32 s8, s0, 0x3ab00c00
	s_addc_u32 s9, s1, 0
	v_writelane_b32 v241, s8, 10
	v_mov_b64_e32 v[146:147], 0x1ff
	s_mov_b32 s51, 0x2aaaaaab
	v_writelane_b32 v241, s9, 11
	s_add_u32 s8, s0, 0x3ab00d00
	s_addc_u32 s9, s1, 0
	v_writelane_b32 v241, s8, 12
	s_movk_i32 s50, 0x4200
	s_movk_i32 s52, 0x3000
	v_writelane_b32 v241, s9, 13
	s_add_u32 s8, s0, 0x3ab00e00
	s_addc_u32 s9, s1, 0
	s_add_u32 s76, s0, 0x3ab00f00
	s_addc_u32 s77, s1, 0
	s_add_u32 s78, s0, 0x3ab01000
	s_addc_u32 s79, s1, 0
	s_add_u32 s80, s0, 0x3ab01100
	s_addc_u32 s81, s1, 0
	s_add_u32 s82, s0, 0x3ab01200
	s_addc_u32 s83, s1, 0
	s_add_u32 s84, s0, 0x3ab01300
	s_addc_u32 s85, s1, 0
	v_writelane_b32 v241, s8, 14
	s_cmp_eq_u32 s33, 15
	s_mov_b32 s54, 0xffff0000
	v_writelane_b32 v241, s9, 15
	s_cselect_b64 s[8:9], -1, 0
	v_writelane_b32 v241, s8, 16
	s_cmp_eq_u32 s33, 14
	s_movk_i32 s55, 0x2100
	v_writelane_b32 v241, s9, 17
	s_cselect_b64 s[8:9], -1, 0
	v_writelane_b32 v241, s8, 18
	s_cmp_eq_u32 s33, 13
	s_mov_b32 s56, 0x800000
	v_writelane_b32 v241, s9, 19
	s_cselect_b64 s[8:9], -1, 0
	v_writelane_b32 v241, s8, 20
	s_cmp_eq_u32 s33, 12
	s_mov_b32 s57, 0xffff
	v_writelane_b32 v241, s9, 21
	s_cselect_b64 s[8:9], -1, 0
	v_writelane_b32 v241, s8, 22
	s_cmp_eq_u32 s33, 11
	s_movk_i32 s58, 0x1ff
	v_writelane_b32 v241, s9, 23
	s_cselect_b64 s[8:9], -1, 0
	v_writelane_b32 v241, s8, 24
	s_cmp_eq_u32 s33, 10
	s_movk_i32 s67, 0x230
	v_writelane_b32 v241, s9, 25
	s_cselect_b64 s[8:9], -1, 0
	v_writelane_b32 v241, s8, 26
	s_cmp_eq_u32 s33, 9
	s_mov_b32 s59, 0x44000
	v_writelane_b32 v241, s9, 27
	s_cselect_b64 s[8:9], -1, 0
	v_writelane_b32 v241, s8, 28
	s_cmp_eq_u32 s33, 8
	s_mov_b32 s60, 0x5040100
	v_writelane_b32 v241, s9, 29
	s_cselect_b64 s[8:9], -1, 0
	v_writelane_b32 v241, s8, 30
	s_cmp_eq_u32 s33, 7
	s_mov_b64 s[16:17], 0x2000
	v_writelane_b32 v241, s9, 31
	s_cselect_b64 s[8:9], -1, 0
	v_writelane_b32 v241, s8, 32
	s_cmp_eq_u32 s33, 6
	s_mov_b64 s[18:19], 0x2a00
	v_writelane_b32 v241, s9, 33
	s_cselect_b64 s[8:9], -1, 0
	v_writelane_b32 v241, s8, 34
	s_cmp_eq_u32 s33, 5
	s_mov_b32 s20, 0x3fb504f3
	v_writelane_b32 v241, s9, 35
	s_cselect_b64 s[8:9], -1, 0
	v_writelane_b32 v241, s8, 36
	s_cmp_eq_u32 s33, 4
	s_nop 0
	v_writelane_b32 v241, s9, 37
	s_cselect_b64 s[8:9], -1, 0
	v_writelane_b32 v241, s8, 38
	s_cmp_eq_u32 s33, 3
	s_nop 0
	v_writelane_b32 v241, s9, 39
	s_cselect_b64 s[8:9], -1, 0
	v_writelane_b32 v241, s8, 40
	s_cmp_eq_u32 s33, 2
	s_nop 0
	v_writelane_b32 v241, s9, 41
	s_cselect_b64 s[8:9], -1, 0
	v_writelane_b32 v241, s8, 42
	s_cmp_eq_u32 s33, 1
	s_nop 0
	v_writelane_b32 v241, s9, 43
	s_cselect_b64 s[8:9], -1, 0
	v_writelane_b32 v241, s8, 44
	s_cmp_eq_u32 s33, 0
	s_nop 0
	v_writelane_b32 v241, s9, 45
	s_cselect_b64 s[8:9], -1, 0
	v_writelane_b32 v241, s8, 46
	s_nop 1
	v_writelane_b32 v241, s9, 47
	s_lshl_b32 s8, s33, 8
	s_add_u32 s8, s86, s8
	s_addc_u32 s9, s87, 0
	s_mov_b64 s[86:87], s[10:11]
	s_add_u32 s10, s8, 0x1400
	s_addc_u32 s11, s9, 0
	v_writelane_b32 v241, s10, 48
	s_add_u32 s8, s8, 0x2400
	s_addc_u32 s9, s9, 0
	v_writelane_b32 v241, s11, 49
	v_writelane_b32 v241, s8, 50
	s_movk_i32 s33, 0x2000
	s_nop 0
	v_writelane_b32 v241, s9, 51
	s_add_u32 s8, s0, 0x3ab03400
;     __device__ bool next(int i, Unit& u) const { if (i != 0) return false; u.pm = pm; u.pn = pn; return true; }
;     __device__ bool next(int i, Unit& u) const { const int L = i * G + c; if (L >= 256) return false; u.pm = L; u.pn = L >> 6; return true; }
;     __device__ bool next(int i, Unit& u) const { Unit t; if (!so.next(i >> 2, t)) return false; const int b = i & 3; u.pm = b * 64 + t.pm; u.pn = b * 8 + t.pn; return true; }
;     __device__ bool next(int i, Unit& u) const {
;         const long L = (long)i * G + c; if (L >= limit) return false;
;         int wgid = (int)L; { const int q = nwg / NXCD, r = nwg % NXCD, xcd = wgid % NXCD, off = wgid / NXCD; wgid = (xcd < r ? xcd * (q + 1) : r * (q + 1) + (xcd - r) * q) + off; }
;         const int nig = WGM * nN, gid = wgid / nig, fm = gid * WGM, gsz = (nM - fm) < WGM ? (nM - fm) : WGM;
;         u.pm = fm + ((wgid % nig) % gsz); u.pn = (wgid % nig) / gsz; return true;
	s_addc_u32 s9, s1, 0
	v_writelane_b32 v241, s8, 52
	s_add_u32 s0, s0, 0x3ab03500
	s_addc_u32 s1, s1, 0
	v_writelane_b32 v241, s9, 53
	v_writelane_b32 v241, s0, 54
	s_nop 1
	v_writelane_b32 v241, s1, 55
	s_nop 0
	v_readlane_b32 s0, v241, 0
	v_readlane_b32 s1, v241, 1
	s_cmpk_lt_i32 s0, 0x100
	s_mov_b32 s8, s0
	s_cselect_b64 s[0:1], -1, 0
	v_writelane_b32 v241, s0, 56
	s_nop 1
	v_writelane_b32 v241, s1, 57
	s_ashr_i32 s1, s8, 31
	s_ashr_i32 s0, s8, 6
	v_writelane_b32 v241, s1, 58
	v_writelane_b32 v241, s0, 59
	s_ashr_i32 s0, s0, 31
	s_cmpk_lt_i32 s3, 0x200
	v_writelane_b32 v241, s0, 60
	s_cselect_b64 s[0:1], -1, 0
	v_writelane_b32 v241, s0, 61
	s_nop 1
	v_writelane_b32 v241, s1, 62
	s_lshl_b32 s1, s8, 3
	v_writelane_b32 v241, s1, 63
	s_lshl_b32 s1, s72, 3
	s_lshl_b32 s0, s6, 6
	v_writelane_b32 v240, s1, 0
	v_readlane_b32 s1, v241, 2
	s_cmp_gt_i32 s1, 7
	s_cselect_b64 s[8:9], -1, 0
	s_cmp_lt_i32 s6, 0
	s_movk_i32 s1, 0x241
	s_cselect_b32 s1, s1, 0x240
	s_mul_i32 s1, s6, s1
	s_mulk_i32 s6, 0x41
	s_cselect_b32 s0, s6, s0
	s_add_i32 s1, s1, s7
	v_writelane_b32 v240, s8, 1
	s_mul_hi_i32 s6, s1, 0x4bda12f7
	s_add_i32 s0, s0, s7
	v_writelane_b32 v240, s9, 2
	s_lshr_b32 s8, s6, 31
	s_ashr_i32 s6, s6, 6
	s_add_i32 s6, s6, s8
	s_mul_i32 s8, s6, 0xd8
	s_sub_i32 s8, s1, s8
	s_mul_hi_i32 s1, s0, 0x2aaaaaab
	s_lshr_b32 s7, s1, 31
	s_ashr_i32 s1, s1, 2
	s_add_i32 s1, s1, s7
	s_mul_i32 s7, s1, 24
	s_mul_i32 s6, s6, 3
	s_sub_i32 s7, s0, s7
	s_sub_i32 s0, 64, s6
	s_min_u32 s9, s0, 3
	v_cvt_f32_ubyte0_e32 v1, s9
	v_cvt_f32_i32_e32 v0, s8
	v_rcp_iflag_f32_e32 v2, v1
	s_mul_i32 s10, s1, 3
	s_sub_i32 s0, 64, s10
	s_min_u32 s11, s0, 3
	v_mul_f32_e32 v2, v0, v2
	v_trunc_f32_e32 v2, v2
	s_ashr_i32 s0, s8, 30
	v_fma_f32 v0, -v2, v1, v0
	s_or_b32 s12, s0, 1
	v_cmp_ge_f32_e64 s[0:1], |v0|, v1
	v_cvt_i32_f32_e32 v0, v2
	s_and_b64 s[0:1], s[0:1], exec
	v_cvt_f32_ubyte0_e32 v1, s11
	s_cselect_b32 s0, s12, 0
	v_readfirstlane_b32 s1, v0
	v_cvt_f32_i32_e32 v0, s7
	v_rcp_iflag_f32_e32 v2, v1
	s_add_i32 s12, s1, s0
	s_mul_i32 s0, s12, s9
	s_sub_i32 s0, s8, s0
	s_sext_i32_i16 s0, s0
	v_mul_f32_e32 v2, v0, v2
	s_mul_i32 s0, s6, 0x48
	s_add_i32 s0, s0, s8
	s_mul_i32 s1, s0, 0xe38f
	s_lshr_b32 s1, s1, 24
	s_mul_i32 s12, s1, 0x120
	s_sub_i32 s12, s0, s12
	s_mul_i32 s0, s0, 0x71c8
	s_lshr_b32 s0, s0, 24
	s_mul_i32 s0, s0, 9
	s_lshl_b32 s1, s1, 2
	s_and_b32 s6, s12, 3
	s_lshr_b32 s12, s12, 2
	s_add_i32 s12, s12, s0
	s_add_i32 s0, s6, s1
	s_cmp_gt_u32 s12, 0x47
	s_cselect_b32 s1, 0x48, 0
	s_sub_i32 s12, s12, s1
	v_trunc_f32_e32 v2, v2
	v_writelane_b32 v240, s0, 3
	s_ashr_i32 s0, s7, 30
	v_fma_f32 v0, -v2, v1, v0
	s_or_b32 s6, s0, 1
	v_cmp_ge_f32_e64 s[0:1], |v0|, v1
	v_cvt_i32_f32_e32 v0, v2
	s_and_b64 s[0:1], s[0:1], exec
	v_writelane_b32 v240, s14, 4
	s_mul_i32 s0, s73, s72
	s_mul_i32 s0, s0, s2
	v_writelane_b32 v240, s15, 5
	v_writelane_b32 v240, s0, 6
	s_cselect_b32 s0, s6, 0
	v_readfirstlane_b32 s1, v0
	s_add_i32 s0, s1, s0
	s_mul_i32 s1, s0, s11
	s_sub_i32 s1, s7, s1
	s_sext_i32_i8 s1, s1
	s_sext_i32_i16 s2, s12
	s_add_i32 s1, s10, s1
	v_writelane_b32 v240, s2, 7
	v_writelane_b32 v240, s1, 8
	s_ashr_i32 s1, s1, 31
	s_sext_i32_i8 s0, s0
	v_writelane_b32 v240, s1, 9
	v_writelane_b32 v240, s0, 10
	s_ashr_i32 s0, s0, 31
	v_writelane_b32 v240, s0, 11
	s_add_i32 s0, 0, 0x23fc0
	v_writelane_b32 v240, s0, 12
	s_add_i32 s0, 0, 0x23fc4
	v_writelane_b32 v240, s0, 13
	s_add_i32 s0, 0, 0x9200
	v_writelane_b32 v240, s0, 14
	s_add_i32 s0, 0, 0x12400
	v_writelane_b32 v240, s0, 15
	s_add_i32 s0, 0, 0x11c00
	v_writelane_b32 v240, s0, 16
	s_mov_b64 s[0:1], -1
	v_writelane_b32 v240, s0, 17
	v_mbcnt_lo_u32_b32 v0, -1, 0
	s_mov_b32 s7, 0
	v_writelane_b32 v240, s1, 18
	v_writelane_b32 v240, s48, 19
	v_cndmask_b32_e64 v167, 0, 1, s[14:15]
	v_mov_b32_e32 v1, 0
	v_writelane_b32 v240, s49, 20
	v_writelane_b32 v240, s62, 21
	v_mbcnt_hi_u32_b32 v172, -1, v0
	s_mov_b32 s73, 0xc1f00000
	v_writelane_b32 v240, s63, 22
	v_writelane_b32 v240, s64, 23
	s_movk_i32 s2, 0x1000
	s_add_i32 s53, 0, 0x23fe0
	v_writelane_b32 v240, s65, 24
	v_writelane_b32 v240, s74, 25
	s_mov_b64 s[8:9], 0x80
	s_mov_b64 s[10:11], 0x1000
	v_writelane_b32 v240, s75, 26
	v_writelane_b32 v240, s86, 27
	s_mov_b32 s12, 0x3a800000
	s_mov_b32 s6, s7
	v_writelane_b32 v240, s87, 28
	v_writelane_b32 v240, s88, 29
	s_nop 1
	v_writelane_b32 v240, s89, 30
	v_writelane_b32 v240, s94, 31
	s_nop 1
	v_writelane_b32 v240, s95, 32
	s_branch .LBB0_216

;     __device__ bool next(int i, Unit& u) const { if (i != 0) return false; u.pm = pm; u.pn = pn; return true; }
;     __device__ bool next(int i, Unit& u) const { const int L = i * G + c; if (L >= 256) return false; u.pm = L; u.pn = L >> 6; return true; }
;     __device__ bool next(int i, Unit& u) const { Unit t; if (!so.next(i >> 2, t)) return false; const int b = i & 3; u.pm = b * 64 + t.pm; u.pn = b * 8 + t.pn; return true; }
;     __device__ bool next(int i, Unit& u) const {
;         const long L = (long)i * G + c; if (L >= limit) return false;
;         int wgid = (int)L; { const int q = nwg / NXCD, r = nwg % NXCD, xcd = wgid % NXCD, off = wgid / NXCD; wgid = (xcd < r ? xcd * (q + 1) : r * (q + 1) + (xcd - r) * q) + off; }
;         const int nig = WGM * nN, gid = wgid / nig, fm = gid * WGM, gsz = (nM - fm) < WGM ? (nM - fm) : WGM;
;         u.pm = fm + ((wgid % nig) % gsz); u.pn = (wgid % nig) / gsz; return true;
.LBB0_227:
	s_add_i32 s66, s66, 1
	s_mul_i32 s24, s66, s21
	s_mul_hi_u32 s40, s66, s72
	s_add_i32 s24, s40, s24
	s_mul_i32 s40, s66, s72
	s_add_u32 s40, s40, s3
	s_addc_u32 s41, s24, s13
	v_cmp_gt_i64_e32 vcc, s[40:41], v[142:143]
	v_cmp_lt_i64_e64 s[42:43], s[40:41], v[140:141]
	s_cbranch_vccnz .LBB0_229
	s_ashr_i32 s24, s40, 31
	s_lshr_b32 s24, s24, 29
	s_add_i32 s24, s40, s24
	s_ashr_i32 s41, s24, 3
	s_and_b32 s24, s24, -8
	s_sub_i32 s24, s40, s24
	s_cmp_lt_i32 s24, 0
	s_cselect_b32 s40, s74, 0x240
	s_mul_i32 s24, s24, s40
	s_add_i32 s24, s24, s41
	s_mul_i32 s40, s24, 0xe38f
	s_lshr_b32 s40, s40, 24
	s_mul_i32 s41, s40, 0x120
	s_mul_i32 s67, s24, 0x71c8
	s_sub_i32 s24, s24, s41
	s_lshr_b32 s67, s67, 24
	s_mul_i32 s67, s67, 9
	s_lshr_b32 s41, s24, 2
	s_add_i32 s67, s67, s41
	s_and_b32 s24, s24, 3
	s_lshl_b32 s40, s40, 2
	s_add_i32 s68, s40, s24
	s_cmp_gt_u32 s67, 0x47
	s_cselect_b32 s41, 0x48, 0
	s_sub_i32 s67, s67, s41
